# v_d1 + P0: waves 4-7 compute their rope-table entries before their x rows (f64 VALU overlaps the other half's streaming)
# speedup vs baseline: 1.0047x; 1.0036x over previous
.LBB0_268:
	s_or_b64 exec, exec, s[8:9]
	s_waitcnt lgkmcnt(0)
	s_barrier
	v_readfirstlane_b32 s75, v184
	v_mov_b32_e32 v66, v17
	s_mov_b32 s74, s3
	s_lshr_b32 s75, s75, 8
.Lp0_setup:
	s_load_dwordx2 s[40:41], s[94:95], 0xd0
	s_load_dwordx2 s[8:9], s[94:95], 0x0
	v_lshlrev_b32_e32 v2, 4, v17
	v_mov_b32_e32 v3, 0
	s_lshl_b32 s4, s2, 4
	s_and_b32 s4, s4, 0x70
	s_waitcnt lgkmcnt(0)
	v_lshl_add_u64 v[4:5], s[8:9], 0, v[2:3]
	v_mbcnt_lo_u32_b32 v2, -1, 0
	v_mbcnt_hi_u32_b32 v46, -1, v2
	v_and_b32_e32 v2, 64, v46
	v_add_u32_e32 v2, 64, v2
	v_xor_b32_e32 v6, 1, v46
	v_cmp_lt_i32_e32 vcc, v6, v2
	s_or_b32 s4, s4, s3
	s_ashr_i32 s12, s2, 6
	v_cndmask_b32_e32 v6, v46, v6, vcc
	v_lshlrev_b32_e32 v11, 2, v6
	v_xor_b32_e32 v6, 2, v46
	v_cmp_lt_i32_e32 vcc, v6, v2
	s_or_b32 s5, s4, 8
	s_mov_b64 s[8:9], 0x3200000
	v_cndmask_b32_e32 v6, v46, v6, vcc
	v_lshlrev_b32_e32 v12, 2, v6
	v_xor_b32_e32 v6, 4, v46
	v_cmp_lt_i32_e32 vcc, v6, v2
	s_mov_b64 s[10:11], 0x2c00000
	v_lshl_add_u32 v10, s12, 3, v1
	v_cndmask_b32_e32 v6, v46, v6, vcc
	v_lshlrev_b32_e32 v13, 2, v6
	v_xor_b32_e32 v6, 8, v46
	v_cmp_lt_i32_e32 vcc, v6, v2
	s_mov_b32 s3, 0
	s_movk_i32 s13, 0x100
	v_cndmask_b32_e32 v6, v46, v6, vcc
	v_lshlrev_b32_e32 v15, 2, v6
	v_xor_b32_e32 v6, 16, v46
	v_cmp_lt_i32_e32 vcc, v6, v2
	v_mov_b32_e32 v19, s4
	s_mov_b32 s14, 0x6050400
	v_cndmask_b32_e32 v6, v46, v6, vcc
	v_lshlrev_b32_e32 v16, 2, v6
	v_xor_b32_e32 v6, 32, v46
	v_cmp_lt_i32_e32 vcc, v6, v2
	s_nop 1
	v_cndmask_b32_e32 v2, v46, v6, vcc
	v_lshlrev_b32_e32 v18, 2, v2
	v_lshlrev_b32_e32 v2, 3, v17
	v_lshl_add_u64 v[6:7], s[40:41], 0, v[2:3]
	v_lshlrev_b32_e32 v2, 2, v17
	v_lshl_add_u64 v[8:9], s[40:41], 0, v[2:3]
	v_lshl_add_u64 v[6:7], v[6:7], 0, s[8:9]
	v_cmp_gt_u32_e32 vcc, 16, v17
	v_cmp_eq_u32_e64 s[8:9], 0, v17
	v_lshl_add_u64 v[8:9], v[8:9], 0, s[10:11]
	v_mov_b32_e32 v17, s5
	s_cmp_eq_u32 s75, 1
	s_cbranch_scc1 .LBB0_272
	s_branch .LBB0_270

.LBB0_272:
	s_cmp_eq_u32 s75, 2
	s_cbranch_scc1 .Lp0_after
	v_lshl_add_u32 v15, s12, 9, v184
	s_movk_i32 s3, 0x1000
	v_cmp_gt_i32_e32 vcc, s3, v15
	s_and_saveexec_b64 s[12:13], vcc
	s_cbranch_execz .LBB0_283
	v_and_b32_e32 v2, 7, v184
	v_lshlrev_b32_e32 v38, 2, v2
	global_load_dword v39, v38, s[94:95] offset:216
	s_load_dwordx2 s[14:15], s[94:95], 0x8
	s_add_u32 s16, s40, 0x2a00000
	s_mov_b32 s20, 0
	s_mov_b32 s22, 0
	s_mov_b32 s24, 0
	s_mov_b32 s42, 0x54442d18
	s_mov_b32 s52, 0x6dc9c883
	s_mov_b32 s54, 0x33145c00
	s_mov_b32 s64, 0x252049c0
	s_mov_b32 s66, 0x46cc5e42
	s_mov_b32 s68, 0x55555555
	s_mov_b32 s70, 0xf9a43bb8
	s_addc_u32 s17, s41, 0
	s_mov_b64 s[18:19], 0
	s_movk_i32 s3, 0x100
	v_mov_b32_e32 v40, s5
	v_mov_b32_e32 v42, s4
	s_mov_b32 s4, 0x6050400
	s_mov_b32 s21, 0x41d00000
	s_mov_b32 s23, 0x7b000000
	s_movk_i32 s5, 0xff80
	s_mov_b32 s25, 0x7ff00000
	v_mov_b32_e32 v3, 0
	s_mov_b32 s27, 0x3ff921fb
	s_mov_b32 s43, 0xbff921fb
	s_mov_b32 s49, 0x3c91a626
	s_mov_b32 s50, 0x33145c07
	s_mov_b32 s53, 0x3fe45f30
	s_mov_b32 s55, 0xbc91a626
	s_mov_b32 s65, 0xb97b839a
	s_mov_b32 s67, 0xbda907db
	s_mov_b32 s69, 0xbfc55555
	s_mov_b32 s71, 0x3de5e0b2
	s_brev_b32 s33, 1
	s_movk_i32 s60, 0x1f8
	s_movk_i32 s61, 0x7ff
	v_mov_b32_e32 v43, 0x40100000
	v_mov_b32_e32 v44, 0x3ff00000
	v_mov_b32_e32 v4, 0x9037ab78
	v_mov_b32_e32 v5, 0x3e21eeb6
	v_mov_b32_e32 v6, 0xa17f65f6
	v_mov_b32_e32 v7, 0xbe927e4f
	v_mov_b32_e32 v8, 0x19f4ec90
	v_mov_b32_e32 v9, 0x3efa01a0
	v_mov_b32_e32 v10, 0x16c16967
	v_mov_b32_e32 v11, 0xbf56c16c
	v_mov_b32_e32 v12, 0x55555555
	v_mov_b32_e32 v13, 0x3fa55555
	v_mov_b32_e32 v16, 0xb42fdfa7
	v_mov_b32_e32 v17, 0xbe5ae600
	v_mov_b32_e32 v18, 0x796cde01
	v_mov_b32_e32 v19, 0x3ec71de3
	v_mov_b32_e32 v20, 0x19e83e5c
	v_mov_b32_e32 v21, 0xbf2a01a0
	s_waitcnt lgkmcnt(0)
	v_mov_b32_e32 v22, 0x11110bb3
	v_mov_b32_e32 v23, 0x3f811111
	v_mov_b32_e32 v45, 0x7ff80000
	s_branch .LBB0_275

.LBB0_283:
	s_or_b64 exec, exec, s[12:13]
	s_cmp_eq_u32 s75, 1
	s_cbranch_scc0 .Lp0_after
	s_mov_b32 s75, 2
	v_mov_b32_e32 v17, v66
	s_mov_b32 s3, s74
	s_branch .Lp0_setup
.Lp0_after:
	s_movk_i32 s3, 0x1800
	v_cmp_gt_i32_e32 vcc, s3, v41
	s_and_saveexec_b64 s[42:43], vcc
	s_cbranch_execz .LBB0_357
	s_movk_i32 s3, 0x84
	v_mov_b32_e32 v4, 0x420
	v_mad_u32_u24 v19, v14, s3, v4
	v_mov_b32_e32 v4, 0x840
	s_load_dwordx8 s[20:27], s[94:95], 0x10
	v_mov_b32_e32 v2, 0x100
	v_mad_u32_u24 v48, v14, s3, v4
	v_lshlrev_b32_e32 v4, 3, v184
	v_lshl_add_u32 v3, v1, 14, v2
	v_lshlrev_b32_e32 v1, 4, v184
	v_and_b32_e32 v18, 56, v4
	s_load_dwordx8 s[12:19], s[94:95], 0xa8
	s_load_dwordx2 s[8:9], s[94:95], 0x30
	v_and_b32_e32 v2, 0x70, v1
	v_mov_b32_e32 v21, 0
	v_lshlrev_b32_e32 v20, 1, v18
	v_add_u32_e32 v1, v3, v2
	v_mad_u32_u24 v54, v18, s3, v3
	v_lshl_add_u64 v[4:5], s[40:41], 0, v[20:21]
	s_mov_b64 s[4:5], 0x1700000
	v_lshrrev_b32_e32 v3, 2, v184
	s_waitcnt lgkmcnt(0)
	v_lshl_add_u64 v[22:23], v[4:5], 0, s[4:5]
	v_and_b32_e32 v3, 8, v3
	s_mov_b64 s[4:5], 0x1200000
	s_cmp_lg_u64 s[26:27], 0
	v_mul_u32_u24_e32 v6, 0x84, v14
	v_and_or_b32 v56, v14, 3, v3
	v_lshl_add_u64 v[24:25], v[4:5], 0, s[4:5]
	s_mov_b64 s[4:5], 0x1900000
	v_mov_b32_e32 v3, v21
	s_cselect_b64 s[48:49], -1, 0
	s_cmp_lg_u64 s[14:15], 0
	v_add_u32_e32 v16, 0x1000, v41
	v_lshl_add_u64 v[26:27], v[4:5], 0, s[4:5]
	s_mov_b64 s[4:5], 0x100000
	v_lshl_add_u64 v[38:39], s[16:17], 0, v[2:3]
	s_cselect_b64 s[16:17], -1, 0
	s_cmp_lg_u64 s[20:21], 0
	v_add_u32_e32 v60, v1, v6
	v_or_b32_e32 v17, 8, v14
	v_or_b32_e32 v47, 16, v14
	v_or_b32_e32 v49, 24, v14
	v_or_b32_e32 v50, 32, v14
	v_or_b32_e32 v51, 40, v14
	v_or_b32_e32 v52, 48, v14
	v_or_b32_e32 v53, 56, v14
	s_mov_b32 s3, 2
	v_lshl_add_u32 v55, v14, 2, v54
	v_or_b32_e32 v57, 4, v56
	v_lshl_add_u64 v[28:29], v[4:5], 0, s[4:5]
	v_lshl_add_u64 v[30:31], s[12:13], 0, v[2:3]
	v_lshl_add_u64 v[32:33], s[8:9], 0, v[2:3]
	s_mov_b64 s[12:13], 0
	v_lshl_add_u64 v[34:35], s[18:19], 0, v[2:3]
	v_lshl_add_u64 v[36:37], s[24:25], 0, v[2:3]
	v_lshl_add_u64 v[40:41], s[22:23], 0, v[2:3]
	s_cselect_b64 s[18:19], -1, 0
	v_mov_b32_e32 v15, v21
	v_lshlrev_b32_e32 v58, 5, v16
	v_lshlrev_b32_e32 v59, 1, v16
	s_movk_i32 s4, 0xaff
	s_movk_i32 s5, 0x15ff
	s_movk_i32 s33, 0x1b7f
	s_movk_i32 s60, 0x20ff
	s_movk_i32 s61, 0x25ff
	v_add_u32_e32 v61, 0x420, v60
	s_mov_b32 s62, 0xffc0
	s_movk_i32 s63, 0x2800
	s_mov_b64 s[22:23], 0x2401500
	s_mov_b64 s[24:25], 0xc01500
	s_movk_i32 s68, 0x5800
	s_mov_b32 s69, 0x2e8ba2e9
	s_movk_i32 s70, 0xff50
	s_movk_i32 s71, 0xea00
	s_movk_i32 s72, 0x1fff
	v_add_u32_e32 v62, 0x428, v60
	v_add_u32_e32 v63, 0x840, v60
	v_add_u32_e32 v64, 0x848, v60
	v_add_u32_e32 v65, 0xc60, v60
	s_branch .LBB0_287
